# v43 + static priority, other half: per-MFMA-block s_setprio flips deleted, waves 0-3 (leading half) raised to prio 1 inside the K-loops
# speedup vs baseline: 1.0011x; 1.0011x over previous
; #define PG8_STAGE(bufoff, gbase, voff) do { _Pragma("unroll") for (int _i = 0; _i < 2; ++_i) \
;         __builtin_amdgcn_global_load_lds((const unsigned*)((const char*)(gbase) + (voff)[_i]), (PG8_LAS unsigned*)(lds + (bufoff) + ldsw + _i * 8192), 16, 0, 0); } while (0)
; #define PG8_LDA(dst, b, h) do { _Pragma("unroll") for (int m = 0; m < 4; ++m) _Pragma("unroll") for (int k = 0; k < 2; ++k) dst[m][k] = *(const PG8_LAS bf16x8*)(lds + PG8_SA(b, h) + aoff + m * 2048 + k * 1024); } while (0)
; #define PG8_LDB(dst, b, h) do { _Pragma("unroll") for (int n = 0; n < 2; ++n) _Pragma("unroll") for (int k = 0; k < 2; ++k) dst[n][k] = *(const PG8_LAS bf16x8*)(lds + PG8_SB(b, h) + boff + n * 2048 + k * 1024); } while (0)
; #define PG8_MMA(ai, bj, At, Bt) do { __builtin_amdgcn_s_setprio(1); _Pragma("unroll") for (int m = 0; m < 4; ++m) _Pragma("unroll") for (int n = 0; n < 2; ++n) _Pragma("unroll") for (int k = 0; k < 2; ++k) \
;         acc[ai][bj][m][n] = mma16<Epi::I8>(Bt[n][k], At[m][k], acc[ai][bj][m][n]); __builtin_amdgcn_s_setprio(0); } while (0)
; #define PG8_WAIT_V(n) asm volatile("s_waitcnt vmcnt(" #n ")" ::: "memory")
; #define PG8_WAIT_L(n) asm volatile("s_waitcnt lgkmcnt(" #n ")" ::: "memory")
; #define PG8_BAR __builtin_amdgcn_s_barrier()
; #define PG8_SCHED __builtin_amdgcn_sched_barrier(0)
; template <class Epi, class Sched, bool ALIGN_EPI = false, bool SP2 = false>
; __device__ __forceinline__ void gemm_phase(PG8_LAS unsigned char* lds, const Gemm g, const Sched& S, const Epi& E) {
;     ...
;             if constexpr (SP2) {
;             PG8_LDB(B0, 0, 0); PG8_LDB(B1, 0, 1); PG8_SCHED; PG8_LDA(At, 0, 0); PG8_STAGE(PG8_SA(1, 1), a1 + hstep, voffA);
;             PG8_WAIT_V(8); PG8_WAIT_L(0); PG8_BAR; PG8_MMA(0, 0, At, B0); PG8_MMA(0, 1, At, B1); PG8_BAR; PG8_SCHED;
.Lpeel80:
	v_readfirstlane_b32 s98, v246
	s_nop 0
	s_bitcmp1_b32 s98, 8
	s_cbranch_scc1 .Lprio80
	s_setprio 1
